# DSA loop: key mask folded into the QK accumulator init as a -1e30 bias (computed under the K-fragment wait, next tile's masks prefetched)
# baseline (speedup 1.0000x reference)
.LBB0_884:
	s_or_b64 exec, exec, s[2:3]
	s_lshl_b32 s38, s58, 5
	v_readlane_b32 s42, v248, 6
	v_readfirstlane_b32 s2, v104
	v_readlane_b32 s43, v248, 7
	v_writelane_b32 v248, s38, 16
	s_lshr_b32 s2, s2, 3
	s_mov_b32 s43, s45
	v_readlane_b32 s41, v248, 12
	s_and_b32 s40, s2, 0x1ffffff8
	s_lshl_b64 s[2:3], s[42:43], 12
	s_mov_b32 s44, s42
	s_lshl_b64 s[42:43], s[42:43], 20
	s_lshl_b32 s39, s41, 19
	s_or_b32 s39, s42, s39
	s_or_b32 s42, s39, 0x800000
	s_lshl_b32 s39, s41, 14
	v_or_b32_e32 v0, s38, v125
	s_or_b32 s39, s39, s2
	s_mov_b32 s56, s47
	s_add_i32 s33, s40, s38
	v_or_b32_e32 v8, s2, v0
	v_mov_b32_e32 v9, s3
	v_readlane_b32 s48, v250, 0
	s_or_b32 s46, s39, 0x90000
	s_mov_b32 s47, s3
	v_lshlrev_b64 v[0:1], 9, v[8:9]
	v_readlane_b32 s52, v250, 4
	v_readlane_b32 s53, v250, 5
	v_or_b32_e32 v80, s33, v168
	s_lshl_b32 s33, s41, 16
	s_lshl_b64 s[46:47], s[46:47], 7
	v_lshl_add_u64 v[146:147], s[52:53], 0, v[0:1]
	v_add_u32_e32 v0, s33, v172
	v_lshl_add_u64 v[148:149], v[138:139], 0, s[46:47]
	s_movk_i32 s48, 0x1000
	v_readlane_b32 s49, v250, 1
	v_or_b32_e32 v8, s2, v0
	v_mov_b32_e32 v81, v117
	v_or_b32_e32 v76, 4, v80
	v_mov_b32_e32 v77, v117
	v_add_co_u32_e32 v24, vcc, s48, v148
	v_lshl_add_u64 v[0:1], v[8:9], 0, v[80:81]
	v_lshl_add_u64 v[8:9], v[8:9], 0, v[76:77]
	v_lshl_add_u64 v[150:151], v[136:137], 0, s[42:43]
	v_addc_co_u32_e32 v25, vcc, 0, v149, vcc
	s_mov_b32 s49, 0x40000
	v_lshlrev_b64 v[0:1], 7, v[0:1]
	v_lshlrev_b64 v[8:9], 7, v[8:9]
	v_add_co_u32_e32 v28, vcc, s49, v150
	v_lshl_add_u64 v[4:5], v[140:141], 0, v[0:1]
	v_lshl_add_u64 v[12:13], v[140:141], 0, v[8:9]
	v_addc_co_u32_e32 v29, vcc, 0, v151, vcc
	s_barrier
	global_load_dwordx4 v[0:3], v[4:5], off
	s_nop 0
	global_load_dwordx4 v[4:7], v[4:5], off offset:64
	s_nop 0
	global_load_dwordx4 v[8:11], v[12:13], off
	s_nop 0
	global_load_dwordx4 v[12:15], v[12:13], off offset:64
	s_nop 0
	global_load_dwordx4 v[16:19], v[148:149], off
	global_load_dwordx4 v[20:23], v[150:151], off
	s_lshr_b32 s38, s58, 1
	global_load_dwordx4 v[24:27], v[24:25], off
	s_nop 0
	global_load_dwordx4 v[28:31], v[28:29], off
	s_nop 0
	global_load_dwordx2 v[32:33], v[146:147], off
	s_cmpk_lt_u32 s56, 0xfc
	s_cselect_b64 s[42:43], -1, 0
	s_and_b64 s[46:47], s[42:43], exec
	v_writelane_b32 v248, s44, 6
	s_cselect_b32 s41, 64, 0
	v_mov_b32_e32 v40, 0
	v_writelane_b32 v248, s45, 7
	s_lshl_b32 s44, s41, 1
	s_mov_b32 s39, 0
	v_lshl_or_b32 v78, s40, 3, v170
	s_add_i32 s40, s38, 1
	v_mov_b32_e32 v41, v40
	v_mov_b32_e32 v42, v40
	v_mov_b32_e32 v43, v40
	v_mov_b32_e32 v44, v40
	v_mov_b32_e32 v45, v40
	v_mov_b32_e32 v46, v40
	v_mov_b32_e32 v47, v40
	v_mov_b32_e32 v52, v40
	v_mov_b32_e32 v53, v40
	v_mov_b32_e32 v54, v40
	v_mov_b32_e32 v55, v40
	v_mov_b32_e32 v34, v40
	v_mov_b32_e32 v35, v40
	v_mov_b32_e32 v48, v40
	v_mov_b32_e32 v49, v40
	s_waitcnt vmcnt(7)
	s_waitcnt vmcnt(5)
	s_waitcnt vmcnt(4)
	ds_write_b128 v127, v[16:19]
	s_waitcnt vmcnt(3)
	ds_write_b128 v127, v[20:23] offset:18432
	s_waitcnt vmcnt(2)
	ds_write_b128 v127, v[24:27] offset:4608
	s_waitcnt vmcnt(1)
	ds_write_b128 v127, v[28:31] offset:23040
	s_waitcnt vmcnt(0)
	ds_write_b64 v169, v[32:33] offset:53376
	v_lshl_add_u64 v[28:29], v[150:151], 0, s[44:45]
	s_lshl_b32 s44, s41, 7
	v_lshl_add_u64 v[24:25], v[148:149], 0, s[44:45]
	global_load_dwordx4 v[16:19], v[24:25], off
	global_load_dwordx4 v[20:23], v[28:29], off
	v_add_co_u32_e32 v24, vcc, s48, v24
	v_cndmask_b32_e64 v32, 0, 1, s[42:43]
	s_nop 0
	v_addc_co_u32_e32 v25, vcc, 0, v25, vcc
	v_add_co_u32_e32 v28, vcc, s49, v28
	v_lshlrev_b32_e32 v32, 3, v32
	v_mov_b32_e32 v33, v117
	v_addc_co_u32_e32 v29, vcc, 0, v29, vcc
	v_lshl_add_u64 v[32:33], v[146:147], 0, v[32:33]
	global_load_dwordx4 v[24:27], v[24:25], off
	v_mov_b32_e32 v50, v40
	global_load_dwordx4 v[28:31], v[28:29], off
	v_mov_b32_e32 v51, v40
	global_load_dwordx2 v[152:153], v[32:33], off
	v_mov_b32_e32 v32, v40
	v_mov_b32_e32 v33, v40
	v_mov_b32_e32 v56, v40
	v_mov_b32_e32 v57, v40
	v_mov_b32_e32 v58, v40
	v_mov_b32_e32 v59, v40
	v_mov_b32_e32 v60, v40
	v_mov_b32_e32 v61, v40
	v_mov_b32_e32 v62, v40
	v_mov_b32_e32 v63, v40
	v_mov_b32_e32 v36, v40
	v_mov_b32_e32 v37, v40
	v_mov_b32_e32 v38, v40
	v_mov_b32_e32 v39, v40
	v_mov_b32_e32 v154, v40
	v_mov_b32_e32 v155, v40
	v_readlane_b32 s50, v250, 2
	v_readlane_b32 s51, v250, 3
	v_readlane_b32 s54, v250, 6
	v_readlane_b32 s55, v250, 7
	v_lshlrev_b32_e32 v199, 4, v104
	ds_write_b128 v199, v[84:87] offset:54016
	s_waitcnt lgkmcnt(0)
	s_barrier
	ds_read_b64 v[212:213], v78 offset:53376
	ds_read_b64 v[246:247], v78 offset:53408
.LBB0_885:
	s_and_b32 s41, s39, 1
	s_xor_b32 s42, s41, 1
	s_mul_i32 s43, s42, 0x2400
	v_add_u32_e32 v199, s43, v127
	s_waitcnt vmcnt(4)
	ds_write_b128 v199, v[16:19]
	s_waitcnt vmcnt(3)
	ds_write_b128 v199, v[20:23] offset:18432
	s_waitcnt vmcnt(1)
	ds_write_b128 v199, v[24:27] offset:4608
	s_waitcnt vmcnt(0)
	ds_write_b128 v199, v[28:31] offset:23040
	v_lshl_or_b32 v217, s42, 8, v169
	ds_write_b64 v217, v[152:153] offset:53376
	v_lshl_add_u32 v217, s41, 8, v78
	s_mulk_i32 s41, 0x2400
	v_add_u32_e32 v251, s41, v129
	v_add_u32_e32 v199, s41, v131
	ds_read_b128 v[218:221], v251 offset:0
	ds_read_b128 v[222:225], v251 offset:64
	ds_read_b128 v[226:229], v251 offset:2304
	ds_read_b128 v[230:233], v251 offset:2368
	ds_read_b128 v[234:237], v251 offset:4608
	ds_read_b128 v[238:241], v251 offset:4672
	ds_read_b128 v[242:245], v251 offset:6912
	ds_read_b128 v[200:203], v251 offset:6976
	s_add_i32 s42, s39, 2
	s_min_i32 s42, s42, s38
	s_lshl_b32 s44, s42, 13
	s_lshl_b32 s46, s42, 7
	s_mov_b32 s47, s45
	s_mov_b32 s43, s45
	v_lshl_add_u64 v[16:17], v[148:149], 0, s[44:45]
	v_lshl_add_u64 v[28:29], v[150:151], 0, s[46:47]
	v_lshl_add_u64 v[152:153], s[42:43], 3, v[146:147]
	global_load_dwordx4 v[16:19], v[16:17], off
	global_load_dwordx4 v[20:23], v[28:29], off
	global_load_dwordx2 v[152:153], v[152:153], off
	s_addk_i32 s44, 0x1000
	s_add_i32 s46, s46, 0x40000
	v_lshl_add_u64 v[24:25], v[148:149], 0, s[44:45]
	v_lshl_add_u64 v[28:29], v[150:151], 0, s[46:47]
	global_load_dwordx4 v[24:27], v[24:25], off
	global_load_dwordx4 v[28:31], v[28:29], off
	s_waitcnt lgkmcnt(13)
	v_lshrrev_b32_e32 v212, v112, v212
	v_lshrrev_b32_e32 v213, v112, v213
	v_lshrrev_b32_e32 v246, v112, v246
	v_lshrrev_b32_e32 v247, v112, v247
	v_not_b32_e32 v212, v212
	v_not_b32_e32 v213, v213
	v_not_b32_e32 v246, v246
	v_not_b32_e32 v247, v247
	v_bfe_i32 v64, v212, 0, 1
	v_bfe_i32 v68, v246, 0, 1
	v_bfe_i32 v65, v212, 1, 1
	v_bfe_i32 v69, v246, 1, 1
	v_bfe_i32 v66, v212, 2, 1
	v_bfe_i32 v70, v246, 2, 1
	v_bfe_i32 v67, v212, 3, 1
	v_bfe_i32 v71, v246, 3, 1
	v_and_b32_e32 v64, 0xf149f2ca, v64
	v_and_b32_e32 v68, 0xf149f2ca, v68
	v_and_b32_e32 v65, 0xf149f2ca, v65
	v_and_b32_e32 v69, 0xf149f2ca, v69
	v_and_b32_e32 v66, 0xf149f2ca, v66
	v_and_b32_e32 v70, 0xf149f2ca, v70
	v_and_b32_e32 v67, 0xf149f2ca, v67
	v_and_b32_e32 v71, 0xf149f2ca, v71
	s_waitcnt lgkmcnt(7)
	v_mfma_f32_16x16x32_bf16 v[64:67], v[218:221], v[0:3], v[64:67]
	v_mfma_f32_16x16x32_bf16 v[68:71], v[218:221], v[8:11], v[68:71]
	v_bfe_i32 v72, v212, 16, 1
	v_bfe_i32 v156, v246, 16, 1
	v_bfe_i32 v73, v212, 17, 1
	v_bfe_i32 v157, v246, 17, 1
	v_bfe_i32 v74, v212, 18, 1
	v_bfe_i32 v158, v246, 18, 1
	v_bfe_i32 v75, v212, 19, 1
	v_bfe_i32 v159, v246, 19, 1
	v_and_b32_e32 v72, 0xf149f2ca, v72
	v_and_b32_e32 v156, 0xf149f2ca, v156
	v_and_b32_e32 v73, 0xf149f2ca, v73
	v_and_b32_e32 v157, 0xf149f2ca, v157
	v_and_b32_e32 v74, 0xf149f2ca, v74
	v_and_b32_e32 v158, 0xf149f2ca, v158
	v_and_b32_e32 v75, 0xf149f2ca, v75
	v_and_b32_e32 v159, 0xf149f2ca, v159
	ds_read_b64 v[194:195], v199 offset:18432
	ds_read_b64 v[196:197], v199 offset:18464
	s_waitcnt lgkmcnt(8)
	v_mfma_f32_16x16x32_bf16 v[64:67], v[222:225], v[4:7], v[64:67]
	v_mfma_f32_16x16x32_bf16 v[68:71], v[222:225], v[12:15], v[68:71]
	s_waitcnt lgkmcnt(7)
	v_mfma_f32_16x16x32_bf16 v[72:75], v[226:229], v[0:3], v[72:75]
	v_mfma_f32_16x16x32_bf16 v[156:159], v[226:229], v[8:11], v[156:159]
	v_bfe_i32 v160, v213, 0, 1
	v_bfe_i32 v182, v247, 0, 1
	v_bfe_i32 v161, v213, 1, 1
	v_bfe_i32 v183, v247, 1, 1
	v_bfe_i32 v162, v213, 2, 1
	v_bfe_i32 v184, v247, 2, 1
	v_bfe_i32 v163, v213, 3, 1
	v_bfe_i32 v185, v247, 3, 1
	v_and_b32_e32 v160, 0xf149f2ca, v160
	v_and_b32_e32 v182, 0xf149f2ca, v182
	v_and_b32_e32 v161, 0xf149f2ca, v161
	v_and_b32_e32 v183, 0xf149f2ca, v183
	v_and_b32_e32 v162, 0xf149f2ca, v162
	v_and_b32_e32 v184, 0xf149f2ca, v184
	v_and_b32_e32 v163, 0xf149f2ca, v163
	v_and_b32_e32 v185, 0xf149f2ca, v185
	ds_read_b64 v[204:205], v199 offset:20736
	ds_read_b64 v[206:207], v199 offset:20768
	s_waitcnt lgkmcnt(8)
	v_mfma_f32_16x16x32_bf16 v[72:75], v[230:233], v[4:7], v[72:75]
	v_mfma_f32_16x16x32_bf16 v[156:159], v[230:233], v[12:15], v[156:159]
	s_waitcnt lgkmcnt(7)
	v_mfma_f32_16x16x32_bf16 v[160:163], v[234:237], v[0:3], v[160:163]
	v_mfma_f32_16x16x32_bf16 v[182:185], v[234:237], v[8:11], v[182:185]
	v_bfe_i32 v186, v213, 16, 1
	v_bfe_i32 v190, v247, 16, 1
	v_bfe_i32 v187, v213, 17, 1
	v_bfe_i32 v191, v247, 17, 1
	v_bfe_i32 v188, v213, 18, 1
	v_bfe_i32 v192, v247, 18, 1
	v_bfe_i32 v189, v213, 19, 1
	v_bfe_i32 v193, v247, 19, 1
	v_and_b32_e32 v186, 0xf149f2ca, v186
	v_and_b32_e32 v190, 0xf149f2ca, v190
	v_and_b32_e32 v187, 0xf149f2ca, v187
	v_and_b32_e32 v191, 0xf149f2ca, v191
	v_and_b32_e32 v188, 0xf149f2ca, v188
	v_and_b32_e32 v192, 0xf149f2ca, v192
	v_and_b32_e32 v189, 0xf149f2ca, v189
	v_and_b32_e32 v193, 0xf149f2ca, v193
	ds_read_b64 v[208:209], v199 offset:23040
	ds_read_b64 v[210:211], v199 offset:23072
	s_waitcnt lgkmcnt(8)
	v_mfma_f32_16x16x32_bf16 v[160:163], v[238:241], v[4:7], v[160:163]
	v_mfma_f32_16x16x32_bf16 v[182:185], v[238:241], v[12:15], v[182:185]
	ds_read_b64 v[218:219], v199 offset:18496
	ds_read_b64 v[220:221], v199 offset:18528
	ds_read_b64 v[222:223], v199 offset:20800
	ds_read_b64 v[224:225], v199 offset:20832
	s_waitcnt lgkmcnt(11)
	v_mfma_f32_16x16x32_bf16 v[186:189], v[242:245], v[0:3], v[186:189]
	v_mfma_f32_16x16x32_bf16 v[190:193], v[242:245], v[8:11], v[190:193]
	ds_read_b64 v[84:85], v199 offset:25344
	ds_read_b64 v[86:87], v199 offset:25376
	s_waitcnt lgkmcnt(12)
	v_mfma_f32_16x16x32_bf16 v[186:189], v[200:203], v[4:7], v[186:189]
	v_mfma_f32_16x16x32_bf16 v[190:193], v[200:203], v[12:15], v[190:193]
	ds_read_b64 v[226:227], v199 offset:23104
	ds_read_b64 v[228:229], v199 offset:23136
	ds_read_b64 v[230:231], v199 offset:25408
	s_waitcnt lgkmcnt(13)
	ds_read_b64 v[232:233], v199 offset:25440
	s_setprio 0
	s_waitcnt lgkmcnt(0)
	s_barrier
	v_exp_f32_e32 v64, v64
	v_exp_f32_e32 v68, v68
	v_exp_f32_e32 v65, v65
	v_exp_f32_e32 v69, v69
	v_exp_f32_e32 v66, v66
	v_exp_f32_e32 v70, v70
	v_exp_f32_e32 v67, v67
	v_exp_f32_e32 v71, v71
	v_add_f32_e32 v155, v155, v64
	v_add_f32_e32 v154, v154, v68
	v_add_f32_e32 v155, v155, v65
	v_add_f32_e32 v154, v154, v69
	v_add_f32_e32 v155, v155, v66
	v_add_f32_e32 v154, v154, v70
	v_add_f32_e32 v155, v155, v67
	v_add_f32_e32 v154, v154, v71
	v_exp_f32_e32 v72, v72
	v_exp_f32_e32 v156, v156
	v_exp_f32_e32 v73, v73
	v_exp_f32_e32 v157, v157
	v_exp_f32_e32 v74, v74
	v_exp_f32_e32 v158, v158
	v_exp_f32_e32 v75, v75
	v_exp_f32_e32 v159, v159
	v_add_f32_e32 v155, v155, v72
	v_add_f32_e32 v154, v154, v156
	v_add_f32_e32 v155, v155, v73
	v_add_f32_e32 v154, v154, v157
	v_add_f32_e32 v155, v155, v74
	v_add_f32_e32 v154, v154, v158
	v_add_f32_e32 v155, v155, v75
	v_add_f32_e32 v154, v154, v159
	v_cvt_pk_bf16_f32 v64, v64, v65
	v_cvt_pk_bf16_f32 v68, v68, v69
	v_cvt_pk_bf16_f32 v65, v66, v67
	v_cvt_pk_bf16_f32 v69, v70, v71
	v_cvt_pk_bf16_f32 v66, v72, v73
	v_cvt_pk_bf16_f32 v70, v156, v157
	v_cvt_pk_bf16_f32 v67, v74, v75
	v_cvt_pk_bf16_f32 v71, v158, v159
	v_exp_f32_e32 v160, v160
	v_exp_f32_e32 v182, v182
	v_mfma_f32_16x16x32_bf16 v[36:39], v[194:197], v[64:67], v[36:39]
	v_exp_f32_e32 v161, v161
	v_exp_f32_e32 v183, v183
	v_exp_f32_e32 v162, v162
	v_exp_f32_e32 v184, v184
	v_exp_f32_e32 v163, v163
	v_mfma_f32_16x16x32_bf16 v[32:35], v[194:197], v[68:71], v[32:35]
	v_exp_f32_e32 v185, v185
	v_add_f32_e32 v155, v155, v160
	v_add_f32_e32 v154, v154, v182
	v_add_f32_e32 v155, v155, v161
	v_add_f32_e32 v154, v154, v183
	v_mfma_f32_16x16x32_bf16 v[60:63], v[204:207], v[64:67], v[60:63]
	v_add_f32_e32 v155, v155, v162
	v_add_f32_e32 v154, v154, v184
	v_add_f32_e32 v155, v155, v163
	v_add_f32_e32 v154, v154, v185
	v_exp_f32_e32 v186, v186
	v_mfma_f32_16x16x32_bf16 v[52:55], v[204:207], v[68:71], v[52:55]
	v_exp_f32_e32 v190, v190
	v_exp_f32_e32 v187, v187
	v_exp_f32_e32 v191, v191
	v_exp_f32_e32 v188, v188
	v_exp_f32_e32 v192, v192
	v_mfma_f32_16x16x32_bf16 v[56:59], v[208:211], v[64:67], v[56:59]
	v_exp_f32_e32 v189, v189
	v_exp_f32_e32 v193, v193
	v_add_f32_e32 v155, v155, v186
	v_add_f32_e32 v154, v154, v190
	v_add_f32_e32 v155, v155, v187
	v_mfma_f32_16x16x32_bf16 v[44:47], v[208:211], v[68:71], v[44:47]
	v_add_f32_e32 v154, v154, v191
	v_add_f32_e32 v155, v155, v188
	v_add_f32_e32 v154, v154, v192
	v_add_f32_e32 v155, v155, v189
	v_add_f32_e32 v154, v154, v193
	v_mfma_f32_16x16x32_bf16 v[48:51], v[84:87], v[64:67], v[48:51]
	v_cvt_pk_bf16_f32 v160, v160, v161
	v_cvt_pk_bf16_f32 v182, v182, v183
	v_cvt_pk_bf16_f32 v161, v162, v163
	v_cvt_pk_bf16_f32 v183, v184, v185
	v_cvt_pk_bf16_f32 v162, v186, v187
	v_mfma_f32_16x16x32_bf16 v[40:43], v[84:87], v[68:71], v[40:43]
	v_cvt_pk_bf16_f32 v184, v190, v191
	v_cvt_pk_bf16_f32 v163, v188, v189
	v_cvt_pk_bf16_f32 v185, v192, v193
	s_add_i32 s39, s39, 1
	s_nop 0
	s_and_b32 s41, s39, 1
	v_lshl_add_u32 v217, s41, 8, v78
	ds_read_b64 v[212:213], v217 offset:53376
	ds_read_b64 v[246:247], v217 offset:53408
	s_setprio 2
	v_mfma_f32_16x16x32_bf16 v[36:39], v[218:221], v[160:163], v[36:39]
	v_mfma_f32_16x16x32_bf16 v[32:35], v[218:221], v[182:185], v[32:35]
	v_mfma_f32_16x16x32_bf16 v[60:63], v[222:225], v[160:163], v[60:63]
	v_mfma_f32_16x16x32_bf16 v[52:55], v[222:225], v[182:185], v[52:55]
	v_mfma_f32_16x16x32_bf16 v[56:59], v[226:229], v[160:163], v[56:59]
	v_mfma_f32_16x16x32_bf16 v[44:47], v[226:229], v[182:185], v[44:47]
	v_mfma_f32_16x16x32_bf16 v[48:51], v[230:233], v[160:163], v[48:51]
	v_mfma_f32_16x16x32_bf16 v[40:43], v[230:233], v[182:185], v[40:43]
	s_cmp_lg_u32 s40, s39
	s_cbranch_scc1 .LBB0_885
	s_setprio 1
	v_lshlrev_b32_e32 v199, 4, v104
	ds_read_b128 v[84:87], v199 offset:54016
	s_waitcnt lgkmcnt(0)
	v_add_u32_e32 v0, s33, v171
	v_or_b32_e32 v0, s2, v0
	v_mov_b32_e32 v1, s3
	v_lshl_add_u64 v[2:3], v[0:1], 0, v[80:81]
	v_lshlrev_b64 v[2:3], 7, v[2:3]
	v_lshl_add_u64 v[2:3], v[142:143], 0, v[2:3]
	global_load_dwordx2 v[4:5], v[2:3], off
	global_load_dwordx2 v[6:7], v[2:3], off offset:32
	global_load_dwordx2 v[8:9], v[2:3], off offset:64
	v_and_b32_e32 v15, 64, v121
	global_load_dwordx2 v[2:3], v[2:3], off offset:96
	v_xor_b32_e32 v14, 16, v121
	v_add_u32_e32 v15, 64, v15
	v_cmp_lt_i32_e32 vcc, v14, v15
	s_waitcnt vmcnt(8)
	v_xor_b32_e32 v16, 32, v121
	v_lshl_add_u64 v[0:1], v[0:1], 0, v[76:77]
	v_cndmask_b32_e32 v14, v121, v14, vcc
	s_waitcnt vmcnt(7)
	v_lshlrev_b32_e32 v20, 2, v14
	ds_bpermute_b32 v14, v20, v155
	v_cmp_lt_i32_e32 vcc, v16, v15
	v_lshlrev_b64 v[0:1], 7, v[0:1]
	v_lshl_add_u64 v[0:1], v[142:143], 0, v[0:1]
	v_cndmask_b32_e32 v15, v121, v16, vcc
	v_lshlrev_b32_e32 v21, 2, v15
	s_waitcnt lgkmcnt(0)
	v_add_f32_e32 v14, v155, v14
	ds_bpermute_b32 v15, v21, v14
	v_readlane_b32 s48, v250, 24
	v_add_u32_e32 v10, s2, v80
	v_mov_b32_e32 v11, v117
	v_readlane_b32 s49, v250, 25
	s_waitcnt lgkmcnt(0)
	v_add_f32_e32 v22, v14, v15
	global_load_dwordx2 v[14:15], v[0:1], off
	global_load_dwordx2 v[16:17], v[0:1], off offset:32
	global_load_dwordx2 v[18:19], v[0:1], off offset:64
	s_nop 0
	global_load_dwordx2 v[0:1], v[0:1], off offset:96
	v_div_scale_f32 v23, s[38:39], v22, v22, 1.0
	s_waitcnt vmcnt(9)
	v_rcp_f32_e32 v24, v23
	v_div_scale_f32 v25, vcc, 1.0, v22, 1.0
	v_readlane_b32 s60, v250, 36
	v_fma_f32 v26, -v23, v24, 1.0
	v_fmac_f32_e32 v24, v26, v24
	v_mul_f32_e32 v26, v25, v24
	v_fma_f32 v27, -v23, v26, v25
	v_fmac_f32_e32 v26, v27, v24
	v_fma_f32 v23, -v23, v26, v25
	v_div_fmas_f32 v23, v23, v24, v26
	v_readlane_b32 s61, v250, 37
	v_div_fixup_f32 v23, v23, v22, 1.0
	v_cmp_lt_f32_e32 vcc, 0, v22
	v_readlane_b32 s3, v248, 12
	v_lshlrev_b64 v[10:11], 11, v[10:11]
	s_mov_b64 s[48:49], s[60:61]
	v_cndmask_b32_e32 v22, 0, v23, vcc
	v_lshl_or_b32 v12, s3, 9, v179
	v_mov_b32_e32 v13, v117
	v_lshl_add_u64 v[10:11], s[48:49], 0, v[10:11]
	v_mul_f32_e32 v23, v36, v22
	v_mul_f32_e32 v24, v37, v22
	v_mul_f32_e32 v26, v39, v22
	v_mov_b32_e32 v145, v117
	v_lshl_add_u64 v[10:11], v[10:11], 0, v[12:13]
	v_mul_f32_e32 v25, v38, v22
	s_waitcnt vmcnt(8)
	v_mul_f32_e32 v28, v61, v22
	v_mul_f32_e32 v30, v63, v22
	v_lshl_add_u64 v[10:11], v[10:11], 0, v[144:145]
	v_mul_f32_e32 v27, v60, v22
	v_mul_f32_e32 v29, v62, v22
	v_mul_f32_e32 v31, v56, v22
	v_readlane_b32 s50, v250, 26
	v_readlane_b32 s51, v250, 27
	v_readlane_b32 s60, v250, 56
	v_readlane_b32 s61, v250, 57
	v_readlane_b32 s50, v248, 20
	v_readlane_b32 s51, v248, 21
	v_readlane_b32 s52, v250, 28
	v_readlane_b32 s53, v250, 29
	v_readlane_b32 s54, v250, 30
	v_readlane_b32 s55, v250, 31
	v_readlane_b32 s56, v250, 32
	v_readlane_b32 s57, v250, 33
	v_readlane_b32 s58, v250, 34
	v_readlane_b32 s59, v250, 35
	v_readlane_b32 s62, v250, 38
	v_readlane_b32 s63, v250, 39
	s_waitcnt vmcnt(7)
	v_lshlrev_b32_e32 v36, 16, v4
	v_and_b32_e32 v4, 0xffff0000, v4
	v_lshlrev_b32_e32 v37, 16, v5
	v_and_b32_e32 v5, 0xffff0000, v5
	s_waitcnt vmcnt(6)
	v_lshlrev_b32_e32 v38, 16, v6
	v_and_b32_e32 v6, 0xffff0000, v6
	v_lshlrev_b32_e32 v39, 16, v7
	v_and_b32_e32 v7, 0xffff0000, v7
	v_mul_f32_e32 v4, v24, v4
	v_mul_f32_e32 v5, v26, v5
	v_mul_f32_e32 v23, v23, v36
	v_mul_f32_e32 v24, v25, v37
	v_mul_f32_e32 v6, v28, v6
	v_mul_f32_e32 v7, v30, v7
	v_cvt_pk_bf16_f32 v4, v23, v4
	v_cvt_pk_bf16_f32 v5, v24, v5
	v_mul_f32_e32 v25, v27, v38
	v_mul_f32_e32 v26, v29, v39
	v_cvt_pk_bf16_f32 v6, v25, v6
	v_cvt_pk_bf16_f32 v7, v26, v7
	global_store_dwordx2 v[10:11], v[4:5], off offset:1024 sc1
	global_store_dwordx2 v[10:11], v[6:7], off offset:1056 sc1
	v_mul_f32_e32 v4, v57, v22
	s_waitcnt vmcnt(7)
	v_and_b32_e32 v5, 0xffff0000, v8
	v_mul_f32_e32 v4, v4, v5
	v_mul_f32_e32 v5, v58, v22
	v_lshlrev_b32_e32 v6, 16, v9
	v_mul_f32_e32 v5, v5, v6
	v_mul_f32_e32 v6, v59, v22
	v_and_b32_e32 v7, 0xffff0000, v9
	v_mul_f32_e32 v6, v6, v7
	v_cvt_pk_bf16_f32 v5, v5, v6
	ds_bpermute_b32 v6, v20, v154
	v_lshlrev_b32_e32 v56, 16, v8
	v_mul_f32_e32 v27, v31, v56
	v_cvt_pk_bf16_f32 v4, v27, v4
	global_store_dwordx2 v[10:11], v[4:5], off offset:1088 sc1
	v_mul_f32_e32 v4, v48, v22
	s_waitcnt vmcnt(7)
	v_lshlrev_b32_e32 v5, 16, v2
	v_mul_f32_e32 v4, v4, v5
	v_mul_f32_e32 v5, v49, v22
	v_and_b32_e32 v2, 0xffff0000, v2
	v_mul_f32_e32 v2, v5, v2
	s_waitcnt lgkmcnt(0)
	v_add_f32_e32 v5, v154, v6
	ds_bpermute_b32 v6, v21, v5
	v_cvt_pk_bf16_f32 v2, v4, v2
	v_mul_f32_e32 v4, v50, v22
	v_lshlrev_b32_e32 v7, 16, v3
	v_mul_f32_e32 v4, v4, v7
	s_waitcnt lgkmcnt(0)
	v_add_f32_e32 v5, v5, v6
	v_div_scale_f32 v6, s[38:39], v5, v5, 1.0
	v_rcp_f32_e32 v8, v6
	v_mul_f32_e32 v7, v51, v22
	v_and_b32_e32 v3, 0xffff0000, v3
	v_mul_f32_e32 v3, v7, v3
	v_cvt_pk_bf16_f32 v3, v4, v3
	global_store_dwordx2 v[10:11], v[2:3], off offset:1120 sc1
	v_fma_f32 v2, -v6, v8, 1.0
	v_fmac_f32_e32 v8, v2, v8
	v_div_scale_f32 v2, vcc, 1.0, v5, 1.0
	v_mul_f32_e32 v3, v2, v8
	v_fma_f32 v4, -v6, v3, v2
	v_fmac_f32_e32 v3, v4, v8
	v_fma_f32 v2, -v6, v3, v2
	v_div_fmas_f32 v2, v2, v8, v3
	v_div_fixup_f32 v2, v2, v5, 1.0
	v_cmp_lt_f32_e32 vcc, 0, v5
	s_waitcnt vmcnt(7)
	v_lshlrev_b32_e32 v5, 16, v14
	v_mov_b32_e32 v3, v117
	v_cndmask_b32_e32 v6, 0, v2, vcc
	v_mul_f32_e32 v4, v32, v6
	v_add_u32_e32 v2, s2, v76
	v_mul_f32_e32 v4, v4, v5
	v_mul_f32_e32 v5, v33, v6
	v_and_b32_e32 v7, 0xffff0000, v14
	v_lshlrev_b64 v[2:3], 11, v[2:3]
	v_mul_f32_e32 v5, v5, v7
	v_lshl_add_u64 v[2:3], s[48:49], 0, v[2:3]
	v_cvt_pk_bf16_f32 v4, v4, v5
	v_mul_f32_e32 v5, v34, v6
	v_lshlrev_b32_e32 v7, 16, v15
	v_lshl_add_u64 v[2:3], v[2:3], 0, v[12:13]
	v_mul_f32_e32 v5, v5, v7
	v_mul_f32_e32 v7, v35, v6
	v_and_b32_e32 v8, 0xffff0000, v15
	v_lshl_add_u64 v[2:3], v[2:3], 0, v[144:145]
	v_mul_f32_e32 v7, v7, v8
	v_cvt_pk_bf16_f32 v5, v5, v7
	global_store_dwordx2 v[2:3], v[4:5], off offset:1024 sc1
	v_mul_f32_e32 v4, v52, v6
	s_waitcnt vmcnt(7)
	v_lshlrev_b32_e32 v5, 16, v16
	v_mul_f32_e32 v4, v4, v5
	v_mul_f32_e32 v5, v53, v6
	v_and_b32_e32 v7, 0xffff0000, v16
	v_mul_f32_e32 v5, v5, v7
	v_cvt_pk_bf16_f32 v4, v4, v5
	v_mul_f32_e32 v5, v54, v6
	v_lshlrev_b32_e32 v7, 16, v17
	v_mul_f32_e32 v5, v5, v7
	v_mul_f32_e32 v7, v55, v6
	v_and_b32_e32 v8, 0xffff0000, v17
	v_mul_f32_e32 v7, v7, v8
	v_cvt_pk_bf16_f32 v5, v5, v7
	global_store_dwordx2 v[2:3], v[4:5], off offset:1056 sc1
	v_mul_f32_e32 v4, v44, v6
	s_waitcnt vmcnt(7)
	v_lshlrev_b32_e32 v5, 16, v18
	v_mul_f32_e32 v4, v4, v5
	v_mul_f32_e32 v5, v45, v6
	v_and_b32_e32 v7, 0xffff0000, v18
	v_mul_f32_e32 v5, v5, v7
	v_cvt_pk_bf16_f32 v4, v4, v5
	v_mul_f32_e32 v5, v46, v6
	v_lshlrev_b32_e32 v7, 16, v19
	v_mul_f32_e32 v5, v5, v7
	v_mul_f32_e32 v7, v47, v6
	v_and_b32_e32 v8, 0xffff0000, v19
	v_mul_f32_e32 v7, v7, v8
	v_cvt_pk_bf16_f32 v5, v5, v7
	global_store_dwordx2 v[2:3], v[4:5], off offset:1088 sc1
	v_mul_f32_e32 v4, v40, v6
	s_waitcnt vmcnt(7)
	v_lshlrev_b32_e32 v5, 16, v0
	v_mul_f32_e32 v4, v4, v5
	v_mul_f32_e32 v5, v41, v6
	v_and_b32_e32 v0, 0xffff0000, v0
	v_mul_f32_e32 v0, v5, v0
	v_cvt_pk_bf16_f32 v0, v4, v0
	v_mul_f32_e32 v4, v42, v6
	v_lshlrev_b32_e32 v5, 16, v1
	v_mul_f32_e32 v4, v4, v5
	v_mul_f32_e32 v5, v43, v6
	v_and_b32_e32 v1, 0xffff0000, v1
	v_mul_f32_e32 v1, v5, v1
	v_cvt_pk_bf16_f32 v1, v4, v1
	global_store_dwordx2 v[2:3], v[0:1], off offset:1120 sc1
	s_waitcnt vmcnt(0)
	s_mov_b64 s[2:3], s[60:61]
	s_barrier
